# normmod row loops (which=1,2): the next row's four loads are issued one iteration ahead (v232..v247) so the row reduce and stores overlap the fetch
# baseline (speedup 1.0000x reference)
; DI void normmod_phase(const P& p, int layer, int which, int nrows, bool first, int vb, int nvb) {
;   const int tid_ = get_tid();
;   const int lane = tid_ & 63, wave = tid_ >> 6;
;   u16* dst = (u16*)(p.ws + OFF_REGA);
;   float* rh = (float*)(p.ws + OFF_RH);
;   const float* mods = (const float*)(p.ws + OFF_MODS) + (size_t)layer * 9 * 9216;
;   const float* g = p.norm_g + ((size_t)layer * 3 + which) * 1024;
;   const int shift_i = which * 3, scale_i = which * 3 + 1;
;   const int nw = nvb * 4;
;   const int per = (nrows + nw - 1) / nw;
;   const int row0 = (vb * 4 + wave) * per;
;   const int row1 = row0 + per < nrows ? row0 + per : nrows;
;   f32x4v gg[4], sh[4], sc1[4];
; #pragma unroll
;   for (int i = 0; i < 4; ++i) {
;     gg[i] = *(const f32x4v*)(g + i * 256 + lane * 4);
;     sh[i] = (f32x4v){0.f, 0.f, 0.f, 0.f};
;     sc1[i] = (f32x4v){1.f, 1.f, 1.f, 1.f};
;   }
;   int crg = -1;
;   for (int row = row0; row < row1; ++row) {
;     const float* src;
;     float* res = row < LAT ? p.out + (size_t)row * 1024 : rh + (size_t)(row - LAT) * 1024;
;     if (first) src = row < LAT ? p.x + (size_t)row * 1024 : p.ctx + (size_t)(row - LAT) * 1024;
;     else src = res;
;     const int rg = row < LAT ? (row >> 11) : 8;
;     if (rg != crg) {
;       const float* mrow = mods + (size_t)rg * 9216;
; #pragma unroll
;       for (int i = 0; i < 4; ++i) {
;         sh[i] = *(const f32x4v*)(mrow + shift_i * 1024 + i * 256 + lane * 4);
;         sc1[i] = *(const f32x4v*)(mrow + scale_i * 1024 + i * 256 + lane * 4) + 1.f;
;         sc1[i] *= gg[i];
;       }
;       crg = rg;
;     }
.LBB0_314:
	s_or_b64 exec, exec, s[0:1]
	v_mov_b32_e32 v16, v132
	s_barrier
	v_readlane_b32 s0, v219, 63
	v_ashrrev_i32_e32 v0, 6, v16
	v_readlane_b32 s1, v218, 0
	v_add_u32_e32 v0, s0, v0
	v_readlane_b32 s0, v219, 43
	s_nop 1
	v_mul_lo_u32 v32, v0, s0
	v_add_u32_e32 v0, s0, v32
	v_min_i32_e32 v35, 0x4800, v0
	v_cmp_lt_i32_e32 vcc, v32, v35
	s_and_saveexec_b64 s[0:1], vcc
	s_cbranch_execz .LBB0_319
	v_lshlrev_b32_e32 v0, 2, v16
	v_and_b32_e32 v34, 0xfc, v0
	v_readlane_b32 s4, v218, 47
	v_lshlrev_b32_e32 v0, 2, v34
	v_mov_b32_e32 v1, v96
	v_readlane_b32 s5, v218, 48
	v_mbcnt_hi_u32_b32 v17, -1, v135
	v_and_b32_e32 v19, 64, v17
	v_lshl_add_u64 v[0:1], s[4:5], 0, v[0:1]
	s_mov_b64 s[4:5], 0x1000
	v_add_co_u32_e32 v8, vcc, 0x1000, v0
	v_lshl_add_u64 v[12:13], v[0:1], 0, s[4:5]
	s_nop 0
	v_addc_co_u32_e32 v9, vcc, 0, v1, vcc
	global_load_dwordx4 v[0:3], v[12:13], off offset:1024
	global_load_dwordx4 v[4:7], v[12:13], off offset:2048
	s_nop 0
	global_load_dwordx4 v[8:11], v[8:9], off
	s_nop 0
	global_load_dwordx4 v[12:15], v[12:13], off offset:3072
	v_xor_b32_e32 v18, 32, v17
	v_add_u32_e32 v19, 64, v19
	v_cmp_lt_i32_e32 vcc, v18, v19
	v_readlane_b32 s4, v223, 61
	v_readlane_b32 s5, v218, 49
	v_cndmask_b32_e32 v18, v17, v18, vcc
	v_lshlrev_b32_e32 v56, 2, v18
	v_xor_b32_e32 v18, 16, v17
	v_cmp_lt_i32_e32 vcc, v18, v19
	v_ashrrev_i32_e32 v33, 31, v32
	s_add_u32 s4, s4, s5
	v_cndmask_b32_e32 v18, v17, v18, vcc
	v_lshlrev_b32_e32 v57, 2, v18
	v_xor_b32_e32 v18, 8, v17
	v_cmp_lt_i32_e32 vcc, v18, v19
	v_readlane_b32 s5, v223, 62
	v_and_b32_e32 v16, 63, v16
	v_cndmask_b32_e32 v18, v17, v18, vcc
	v_lshlrev_b32_e32 v58, 2, v18
	v_xor_b32_e32 v18, 4, v17
	v_cmp_lt_i32_e32 vcc, v18, v19
	v_readlane_b32 s16, v223, 59
	s_addc_u32 s5, s5, 0
	v_cndmask_b32_e32 v18, v17, v18, vcc
	v_lshlrev_b32_e32 v59, 2, v18
	v_xor_b32_e32 v18, 2, v17
	v_cmp_lt_i32_e32 vcc, v18, v19
	v_readlane_b32 s17, v223, 60
	v_mov_b32_e32 v97, v96
	v_cndmask_b32_e32 v18, v17, v18, vcc
	v_lshlrev_b32_e32 v60, 2, v18
	v_xor_b32_e32 v18, 1, v17
	v_cmp_lt_i32_e32 vcc, v18, v19
	s_add_u32 s4, s4, 0x3000
	s_waitcnt vmcnt(14)
	v_mov_b32_e32 v98, v96
	v_cndmask_b32_e32 v17, v17, v18, vcc
	v_lshlrev_b64 v[18:19], 11, v[32:33]
	v_lshl_or_b32 v18, v16, 3, v18
	v_lshlrev_b32_e32 v61, 2, v17
	v_lshl_add_u64 v[36:37], s[16:17], 0, v[18:19]
	v_mov_b32_e32 v99, v96
	v_mov_b32_e32 v38, 1.0
	v_mov_b64_e32 v[16:17], v[96:97]
	v_mov_b64_e32 v[20:21], v[96:97]
	v_mov_b64_e32 v[24:25], v[96:97]
	v_mov_b64_e32 v[28:29], v[96:97]
	s_addc_u32 s5, s5, 0
	v_mov_b32_e32 v62, -1
	s_mov_b64 s[38:39], 0
	v_mov_b64_e32 v[18:19], v[98:99]
	v_mov_b64_e32 v[22:23], v[98:99]
	v_mov_b64_e32 v[26:27], v[98:99]
	v_mov_b64_e32 v[30:31], v[98:99]
	v_mov_b32_e32 v39, v38
	v_mov_b32_e32 v48, v38
	s_waitcnt vmcnt(5)
	v_mov_b32_e32 v49, v38
	v_mov_b32_e32 v40, v38
	v_mov_b32_e32 v41, v38
	v_mov_b32_e32 v42, v38
	v_mov_b32_e32 v43, v38
	v_mov_b32_e32 v44, v38
	v_mov_b32_e32 v45, v38
	v_mov_b32_e32 v46, v38
	v_mov_b32_e32 v47, v38
	v_mov_b32_e32 v50, v38
	v_mov_b32_e32 v51, v38
	v_mov_b32_e32 v52, v38
	v_mov_b32_e32 v53, v38
	v_lshlrev_b32_e32 v54, 2, v34
	v_cmp_gt_i32_e32 vcc, s8, v32
	v_add_u32_e32 v55, 0xffffc000, v32
	v_mov_b32_e32 v63, s69
	v_cndmask_b32_e32 v64, v55, v32, vcc
	v_mov_b32_e32 v55, s33
	v_cndmask_b32_e32 v65, 0, v33, vcc
	v_cndmask_b32_e32 v67, v55, v63, vcc
	v_mov_b32_e32 v55, s3
	v_mov_b32_e32 v63, s68
	v_cndmask_b32_e32 v66, v55, v63, vcc
	v_lshlrev_b64 v[64:65], 12, v[64:65]
	v_lshl_add_u64 v[64:65], v[66:67], 0, v[64:65]
	v_mov_b32_e32 v55, v96
	v_lshl_add_u64 v[248:249], v[64:65], 0, v[54:55]
	global_load_dwordx4 v[232:235], v[248:249], off
	global_load_dwordx4 v[236:239], v[248:249], off offset:1024
	global_load_dwordx4 v[240:243], v[248:249], off offset:2048
	global_load_dwordx4 v[244:247], v[248:249], off offset:3072
	s_branch .LBB0_317
; DI void normmod_phase(const P& p, int layer, int which, int nrows, bool first, int vb, int nvb) {
;     ...
;   for (int row = row0; row < row1; ++row) {
;     const float* src;
;     float* res = row < LAT ? p.out + (size_t)row * 1024 : rh + (size_t)(row - LAT) * 1024;
;     if (first) src = row < LAT ? p.x + (size_t)row * 1024 : p.ctx + (size_t)(row - LAT) * 1024;
;     else src = res;
;     const int rg = row < LAT ? (row >> 11) : 8;
;     if (rg != crg) {
;       const float* mrow = mods + (size_t)rg * 9216;
; #pragma unroll
;       for (int i = 0; i < 4; ++i) {
;         sh[i] = *(const f32x4v*)(mrow + shift_i * 1024 + i * 256 + lane * 4);
;         sc1[i] = *(const f32x4v*)(mrow + scale_i * 1024 + i * 256 + lane * 4) + 1.f;
;         sc1[i] *= gg[i];
;       }
;       crg = rg;
;     }
;     f32x4v v[4];
;     float ss = 0.f;
; #pragma unroll
;     for (int i = 0; i < 4; ++i) {
;       v[i] = *(const f32x4v*)(src + i * 256 + lane * 4);
;       ss += v[i].x * v[i].x + v[i].y * v[i].y + v[i].z * v[i].z + v[i].w * v[i].w;
;     }
;     ss = wave_sum(ss);
;     const float rinv = rsqrtf(ss * (1.f / 1024.f) + EPS);
; #pragma unroll
;     for (int i = 0; i < 4; ++i) {
;       const int col = i * 256 + lane * 4;
;       if (first) *(f32x4v*)(res + col) = v[i];
;       const f32x4v y = v[i] * rinv * sc1[i] + sh[i];
;       uint2 o;
;       o.x = pack2(y.x, y.y); o.y = pack2(y.z, y.w);
;       *(uint2*)(dst + (size_t)row * 1024 + col) = o;
;     }
;   }
.LBB0_316:
	s_or_b64 exec, exec, s[42:43]
	s_waitcnt vmcnt(4)
	v_mov_b32_e32 v64, v232
	v_mov_b32_e32 v65, v233
	v_mov_b32_e32 v66, v234
	v_mov_b32_e32 v67, v235
	v_mov_b32_e32 v68, v236
	v_mov_b32_e32 v69, v237
	v_mov_b32_e32 v70, v238
	v_mov_b32_e32 v71, v239
	v_mov_b32_e32 v224, v240
	v_mov_b32_e32 v225, v241
	v_mov_b32_e32 v226, v242
	v_mov_b32_e32 v227, v243
	v_mov_b32_e32 v228, v244
	v_mov_b32_e32 v229, v245
	v_mov_b32_e32 v230, v246
	v_mov_b32_e32 v231, v247
	v_add_u32_e32 v250, 1, v32
	v_cmp_gt_i32_e32 vcc, s8, v250
	v_add_u32_e32 v55, 0xffffc000, v250
	v_mov_b32_e32 v63, s69
	v_cndmask_b32_e32 v72, v55, v250, vcc
	v_mov_b32_e32 v55, s33
	v_cndmask_b32_e32 v73, 0, v33, vcc
	v_cndmask_b32_e32 v75, v55, v63, vcc
	v_mov_b32_e32 v55, s3
	v_mov_b32_e32 v63, s68
	v_cndmask_b32_e32 v74, v55, v63, vcc
	v_lshlrev_b64 v[72:73], 12, v[72:73]
	v_lshl_add_u64 v[72:73], v[74:75], 0, v[72:73]
	v_mov_b32_e32 v55, v96
	v_lshl_add_u64 v[248:249], v[72:73], 0, v[54:55]
	global_load_dwordx4 v[232:235], v[248:249], off
	global_load_dwordx4 v[236:239], v[248:249], off offset:1024
	global_load_dwordx4 v[240:243], v[248:249], off offset:2048
	global_load_dwordx4 v[244:247], v[248:249], off offset:3072
	v_lshl_add_u64 v[32:33], v[32:33], 0, 1
	s_mov_b64 s[16:17], 0x800
	v_mov_b32_e32 v74, v65
	v_mov_b32_e32 v75, v69
	v_mov_b32_e32 v72, v64
	v_mov_b32_e32 v73, v68
	v_pk_mul_f32 v[74:75], v[74:75], v[74:75]
	s_nop 0
	v_pk_fma_f32 v[72:73], v[72:73], v[72:73], v[74:75]
	v_mov_b32_e32 v74, v66
	v_mov_b32_e32 v75, v70
	v_pk_fma_f32 v[72:73], v[74:75], v[74:75], v[72:73]
	v_mov_b32_e32 v74, v67
	v_mov_b32_e32 v75, v71
	v_pk_fma_f32 v[80:81], v[74:75], v[74:75], v[72:73]
	v_add_f32_e32 v63, v80, v81
	v_mov_b32_e32 v82, v225
	v_mov_b32_e32 v83, v229
	v_mov_b32_e32 v54, v224
	v_mov_b32_e32 v55, v228
	v_pk_mul_f32 v[82:83], v[82:83], v[82:83]
	s_nop 0
	v_pk_fma_f32 v[54:55], v[54:55], v[54:55], v[82:83]
	v_mov_b32_e32 v82, v226
	v_mov_b32_e32 v83, v230
	v_pk_fma_f32 v[54:55], v[82:83], v[82:83], v[54:55]
	v_mov_b32_e32 v82, v227
	v_mov_b32_e32 v83, v231
	v_pk_fma_f32 v[54:55], v[82:83], v[82:83], v[54:55]
	s_nop 0
	v_add_f32_e32 v54, v63, v54
	v_add_f32_e32 v54, v54, v55
	s_nop 1
	v_add_f32_dpp v54, v54, v54 quad_perm:[1,0,3,2] row_mask:0xf bank_mask:0xf
	s_nop 1
	v_add_f32_dpp v54, v54, v54 quad_perm:[2,3,0,1] row_mask:0xf bank_mask:0xf
	s_nop 1
	v_add_f32_dpp v54, v54, v54 row_half_mirror row_mask:0xf bank_mask:0xf
	s_nop 1
	v_add_f32_dpp v54, v54, v54 row_mirror row_mask:0xf bank_mask:0xf
	s_nop 1
	v_add_f32_dpp v54, v54, v54 row_bcast:15 row_mask:0xa bank_mask:0xf
	s_nop 1
	v_add_f32_dpp v54, v54, v54 row_bcast:31 row_mask:0xc bank_mask:0xf
	s_nop 1
	v_readlane_b32 s100, v54, 63
	s_nop 3
	v_mov_b32_e32 v54, s100
	v_fmamk_f32 v54, v54, 0x3a800000, v119
	v_cmp_gt_f32_e32 vcc, s9, v54
	v_mul_f32_e32 v55, 0x4b800000, v54
	s_nop 0
	v_cndmask_b32_e32 v54, v54, v55, vcc
	v_rsq_f32_e32 v54, v54
	s_nop 0
	v_mul_f32_e32 v55, 0x45800000, v54
	v_cndmask_b32_e32 v54, v54, v55, vcc
	s_waitcnt vmcnt(4)
	v_pk_mul_f32 v[64:65], v[64:65], v[54:55] op_sel_hi:[1,0]
	v_pk_mul_f32 v[66:67], v[66:67], v[54:55] op_sel_hi:[1,0]
	v_pk_fma_f32 v[64:65], v[38:39], v[64:65], v[28:29]
	v_pk_fma_f32 v[66:67], v[48:49], v[66:67], v[30:31]
	v_cvt_pk_bf16_f32 v64, v64, v65
	v_cvt_pk_bf16_f32 v65, v66, v67
	global_store_dwordx2 v[36:37], v[64:65], off
	v_pk_mul_f32 v[64:65], v[68:69], v[54:55] op_sel_hi:[1,0]
	v_pk_mul_f32 v[66:67], v[70:71], v[54:55] op_sel_hi:[1,0]
	v_pk_fma_f32 v[64:65], v[40:41], v[64:65], v[24:25]
	v_pk_fma_f32 v[66:67], v[42:43], v[66:67], v[26:27]
	v_cvt_pk_bf16_f32 v64, v64, v65
	v_cvt_pk_bf16_f32 v65, v66, v67
	global_store_dwordx2 v[36:37], v[64:65], off offset:512
	v_pk_mul_f32 v[64:65], v[224:225], v[54:55] op_sel_hi:[1,0]
	v_pk_mul_f32 v[66:67], v[226:227], v[54:55] op_sel_hi:[1,0]
	v_pk_fma_f32 v[64:65], v[44:45], v[64:65], v[20:21]
	v_pk_fma_f32 v[66:67], v[46:47], v[66:67], v[22:23]
	v_cvt_pk_bf16_f32 v64, v64, v65
	v_cvt_pk_bf16_f32 v65, v66, v67
	global_store_dwordx2 v[36:37], v[64:65], off offset:1024
	v_pk_mul_f32 v[64:65], v[228:229], v[54:55] op_sel_hi:[1,0]
	v_pk_mul_f32 v[54:55], v[230:231], v[54:55] op_sel_hi:[1,0]
	v_pk_fma_f32 v[64:65], v[50:51], v[64:65], v[16:17]
	v_pk_fma_f32 v[54:55], v[52:53], v[54:55], v[18:19]
	v_cvt_pk_bf16_f32 v64, v64, v65
	v_cvt_pk_bf16_f32 v65, v54, v55
	v_cmp_ge_i32_e32 vcc, v32, v35
	global_store_dwordx2 v[36:37], v[64:65], off offset:1536
	v_lshl_add_u64 v[36:37], v[36:37], 0, s[16:17]
	s_or_b64 s[38:39], vcc, s[38:39]
	s_andn2_b64 exec, exec, s[38:39]
	s_cbranch_execz .LBB0_319

; DI void normmod_phase(const P& p, int layer, int which, int nrows, bool first, int vb, int nvb) {
;   const int tid_ = get_tid();
;   const int lane = tid_ & 63, wave = tid_ >> 6;
;   u16* dst = (u16*)(p.ws + OFF_REGA);
;   float* rh = (float*)(p.ws + OFF_RH);
;   const float* mods = (const float*)(p.ws + OFF_MODS) + (size_t)layer * 9 * 9216;
;   const float* g = p.norm_g + ((size_t)layer * 3 + which) * 1024;
;   const int shift_i = which * 3, scale_i = which * 3 + 1;
;   const int nw = nvb * 4;
;   const int per = (nrows + nw - 1) / nw;
;   const int row0 = (vb * 4 + wave) * per;
;   const int row1 = row0 + per < nrows ? row0 + per : nrows;
;   f32x4v gg[4], sh[4], sc1[4];
; #pragma unroll
;   for (int i = 0; i < 4; ++i) {
;     gg[i] = *(const f32x4v*)(g + i * 256 + lane * 4);
;     sh[i] = (f32x4v){0.f, 0.f, 0.f, 0.f};
;     sc1[i] = (f32x4v){1.f, 1.f, 1.f, 1.f};
;   }
;   int crg = -1;
.LBB0_1348:
	v_readlane_b32 s0, v220, 53
	s_add_i32 s0, s0, s20
	s_ashr_i32 s1, s0, 31
	v_readlane_b32 s4, v219, 41
	s_xor_b32 s1, s1, s4
	s_abs_i32 s0, s0
	v_readlane_b32 s4, v219, 40
	s_mul_hi_u32 s4, s0, s4
	v_readlane_b32 s16, v219, 42
	s_mul_i32 s5, s4, s16
	s_sub_i32 s0, s0, s5
	s_add_i32 s5, s4, 1
	s_sub_i32 s15, s0, s16
	s_cmp_ge_u32 s0, s16
	s_cselect_b32 s4, s5, s4
	s_cselect_b32 s0, s15, s0
	s_add_i32 s5, s4, 1
	s_cmp_ge_u32 s0, s16
	v_mov_b32_e32 v16, v132
	s_cselect_b32 s0, s5, s4
	s_xor_b32 s0, s0, s1
	v_ashrrev_i32_e32 v0, 6, v16
	v_readlane_b32 s4, v219, 63
	s_sub_i32 s0, s0, s1
	v_readlane_b32 s5, v218, 0
	v_add_u32_e32 v0, s4, v0
	v_mul_lo_u32 v32, v0, s0
	v_add_u32_e32 v0, s0, v32
	v_min_i32_e32 v35, s20, v0
	v_cmp_lt_i32_e32 vcc, v32, v35
	s_and_saveexec_b64 s[0:1], vcc
	s_cbranch_execz .LBB0_1353
	v_lshlrev_b32_e32 v0, 2, v16
	v_and_b32_e32 v34, 0xfc, v0
	v_readlane_b32 s4, v218, 47
	v_lshlrev_b32_e32 v0, 2, v34
	v_mov_b32_e32 v1, v96
	v_readlane_b32 s5, v218, 48
	v_ashrrev_i32_e32 v33, 31, v32
	v_lshlrev_b64 v[18:19], 11, v[32:33]
	v_lshl_add_u64 v[0:1], s[4:5], 0, v[0:1]
	s_mov_b64 s[4:5], 0x2000
	v_add_co_u32_e32 v8, vcc, 0x2000, v0
	v_lshl_add_u64 v[12:13], v[0:1], 0, s[4:5]
	s_nop 0
	v_addc_co_u32_e32 v9, vcc, 0, v1, vcc
	global_load_dwordx4 v[0:3], v[12:13], off offset:1024
	global_load_dwordx4 v[4:7], v[12:13], off offset:2048
	s_nop 0
	global_load_dwordx4 v[8:11], v[8:9], off
	s_nop 0
	global_load_dwordx4 v[12:15], v[12:13], off offset:3072
	v_cmp_lt_i32_e32 vcc, v137, v139
	v_readlane_b32 s4, v223, 61
	v_readlane_b32 s5, v218, 49
	v_cndmask_b32_e32 v17, v136, v137, vcc
	v_cmp_lt_i32_e32 vcc, v140, v139
	v_lshlrev_b32_e32 v56, 2, v17
	s_add_u32 s4, s4, s5
	v_cndmask_b32_e32 v17, v136, v140, vcc
	v_cmp_lt_i32_e32 vcc, v141, v139
	v_lshlrev_b32_e32 v57, 2, v17
	v_readlane_b32 s5, v223, 62
	v_cndmask_b32_e32 v17, v136, v141, vcc
	v_cmp_lt_i32_e32 vcc, v142, v139
	v_lshlrev_b32_e32 v58, 2, v17
	v_and_b32_e32 v16, 63, v16
	v_cndmask_b32_e32 v17, v136, v142, vcc
	v_cmp_lt_i32_e32 vcc, v143, v139
	v_lshlrev_b32_e32 v59, 2, v17
	v_readlane_b32 s16, v223, 59
	v_cndmask_b32_e32 v17, v136, v143, vcc
	v_cmp_lt_i32_e32 vcc, v144, v139
	s_addc_u32 s5, s5, 0
	v_lshlrev_b32_e32 v60, 2, v17
	v_cndmask_b32_e32 v17, v136, v144, vcc
	v_lshl_or_b32 v18, v16, 3, v18
	v_readlane_b32 s17, v223, 60
	v_mov_b32_e32 v97, v96
	s_add_u32 s4, s4, 0x6000
	v_lshlrev_b32_e32 v61, 2, v17
	v_lshl_add_u64 v[36:37], s[16:17], 0, v[18:19]
	s_waitcnt vmcnt(14)
	v_mov_b32_e32 v98, v96
	v_mov_b32_e32 v99, v96
	v_mov_b32_e32 v38, 1.0
	v_mov_b64_e32 v[16:17], v[96:97]
	v_mov_b64_e32 v[20:21], v[96:97]
	v_mov_b64_e32 v[24:25], v[96:97]
	v_mov_b64_e32 v[28:29], v[96:97]
	s_addc_u32 s5, s5, 0
	v_mov_b32_e32 v62, -1
	s_mov_b64 s[38:39], 0
	v_mov_b64_e32 v[18:19], v[98:99]
	v_mov_b64_e32 v[22:23], v[98:99]
	v_mov_b64_e32 v[26:27], v[98:99]
	v_mov_b64_e32 v[30:31], v[98:99]
	v_mov_b32_e32 v39, v38
	v_mov_b32_e32 v48, v38
	s_waitcnt vmcnt(5)
	v_mov_b32_e32 v49, v38
	v_mov_b32_e32 v40, v38
	v_mov_b32_e32 v41, v38
	v_mov_b32_e32 v42, v38
	v_mov_b32_e32 v43, v38
	v_mov_b32_e32 v44, v38
	v_mov_b32_e32 v45, v38
	v_mov_b32_e32 v46, v38
	v_mov_b32_e32 v47, v38
	v_mov_b32_e32 v50, v38
	v_mov_b32_e32 v51, v38
	v_mov_b32_e32 v52, v38
	v_mov_b32_e32 v53, v38
	v_lshlrev_b32_e32 v54, 2, v34
	v_cmp_gt_i32_e32 vcc, s8, v32
	v_add_u32_e32 v55, 0xffffc000, v32
	v_mov_b32_e32 v63, s69
	v_cndmask_b32_e32 v64, v55, v32, vcc
	v_mov_b32_e32 v55, s33
	v_cndmask_b32_e32 v65, 0, v33, vcc
	v_cndmask_b32_e32 v67, v55, v63, vcc
	v_mov_b32_e32 v55, s3
	v_mov_b32_e32 v63, s68
	v_cndmask_b32_e32 v66, v55, v63, vcc
	v_lshlrev_b64 v[64:65], 12, v[64:65]
	v_lshl_add_u64 v[64:65], v[66:67], 0, v[64:65]
	v_mov_b32_e32 v55, v96
	v_lshl_add_u64 v[248:249], v[64:65], 0, v[54:55]
	global_load_dwordx4 v[232:235], v[248:249], off
	global_load_dwordx4 v[236:239], v[248:249], off offset:1024
	global_load_dwordx4 v[240:243], v[248:249], off offset:2048
	global_load_dwordx4 v[244:247], v[248:249], off offset:3072
	s_branch .LBB0_1351
; DI void normmod_phase(const P& p, int layer, int which, int nrows, bool first, int vb, int nvb) {
;     ...
;   for (int row = row0; row < row1; ++row) {
;     const float* src;
;     float* res = row < LAT ? p.out + (size_t)row * 1024 : rh + (size_t)(row - LAT) * 1024;
;     if (first) src = row < LAT ? p.x + (size_t)row * 1024 : p.ctx + (size_t)(row - LAT) * 1024;
;     else src = res;
;     const int rg = row < LAT ? (row >> 11) : 8;
;     if (rg != crg) {
;       const float* mrow = mods + (size_t)rg * 9216;
; #pragma unroll
;       for (int i = 0; i < 4; ++i) {
;         sh[i] = *(const f32x4v*)(mrow + shift_i * 1024 + i * 256 + lane * 4);
;         sc1[i] = *(const f32x4v*)(mrow + scale_i * 1024 + i * 256 + lane * 4) + 1.f;
;         sc1[i] *= gg[i];
;       }
;       crg = rg;
;     }
;     f32x4v v[4];
;     float ss = 0.f;
; #pragma unroll
;     for (int i = 0; i < 4; ++i) {
;       v[i] = *(const f32x4v*)(src + i * 256 + lane * 4);
;       ss += v[i].x * v[i].x + v[i].y * v[i].y + v[i].z * v[i].z + v[i].w * v[i].w;
;     }
;     ss = wave_sum(ss);
;     const float rinv = rsqrtf(ss * (1.f / 1024.f) + EPS);
; #pragma unroll
;     for (int i = 0; i < 4; ++i) {
;       const int col = i * 256 + lane * 4;
;       if (first) *(f32x4v*)(res + col) = v[i];
;       const f32x4v y = v[i] * rinv * sc1[i] + sh[i];
;       uint2 o;
;       o.x = pack2(y.x, y.y); o.y = pack2(y.z, y.w);
;       *(uint2*)(dst + (size_t)row * 1024 + col) = o;
;     }
;   }
.LBB0_1350:
	s_or_b64 exec, exec, s[40:41]
	s_waitcnt vmcnt(4)
	v_mov_b32_e32 v64, v232
	v_mov_b32_e32 v65, v233
	v_mov_b32_e32 v66, v234
	v_mov_b32_e32 v67, v235
	v_mov_b32_e32 v68, v236
	v_mov_b32_e32 v69, v237
	v_mov_b32_e32 v70, v238
	v_mov_b32_e32 v71, v239
	v_mov_b32_e32 v224, v240
	v_mov_b32_e32 v225, v241
	v_mov_b32_e32 v226, v242
	v_mov_b32_e32 v227, v243
	v_mov_b32_e32 v228, v244
	v_mov_b32_e32 v229, v245
	v_mov_b32_e32 v230, v246
	v_mov_b32_e32 v231, v247
	v_add_u32_e32 v250, 1, v32
	v_cmp_gt_i32_e32 vcc, s8, v250
	v_add_u32_e32 v55, 0xffffc000, v250
	v_mov_b32_e32 v63, s69
	v_cndmask_b32_e32 v72, v55, v250, vcc
	v_mov_b32_e32 v55, s33
	v_cndmask_b32_e32 v73, 0, v33, vcc
	v_cndmask_b32_e32 v75, v55, v63, vcc
	v_mov_b32_e32 v55, s3
	v_mov_b32_e32 v63, s68
	v_cndmask_b32_e32 v74, v55, v63, vcc
	v_lshlrev_b64 v[72:73], 12, v[72:73]
	v_lshl_add_u64 v[72:73], v[74:75], 0, v[72:73]
	v_mov_b32_e32 v55, v96
	v_lshl_add_u64 v[248:249], v[72:73], 0, v[54:55]
	global_load_dwordx4 v[232:235], v[248:249], off
	global_load_dwordx4 v[236:239], v[248:249], off offset:1024
	global_load_dwordx4 v[240:243], v[248:249], off offset:2048
	global_load_dwordx4 v[244:247], v[248:249], off offset:3072
	v_lshl_add_u64 v[32:33], v[32:33], 0, 1
	s_mov_b64 s[16:17], 0x800
	v_mov_b32_e32 v74, v65
	v_mov_b32_e32 v75, v69
	v_mov_b32_e32 v72, v64
	v_mov_b32_e32 v73, v68
	v_pk_mul_f32 v[74:75], v[74:75], v[74:75]
	s_nop 0
	v_pk_fma_f32 v[72:73], v[72:73], v[72:73], v[74:75]
	v_mov_b32_e32 v74, v66
	v_mov_b32_e32 v75, v70
	v_pk_fma_f32 v[72:73], v[74:75], v[74:75], v[72:73]
	v_mov_b32_e32 v74, v67
	v_mov_b32_e32 v75, v71
	v_pk_fma_f32 v[80:81], v[74:75], v[74:75], v[72:73]
	v_add_f32_e32 v63, v80, v81
	v_mov_b32_e32 v82, v225
	v_mov_b32_e32 v83, v229
	v_mov_b32_e32 v54, v224
	v_mov_b32_e32 v55, v228
	v_pk_mul_f32 v[82:83], v[82:83], v[82:83]
	s_nop 0
	v_pk_fma_f32 v[54:55], v[54:55], v[54:55], v[82:83]
	v_mov_b32_e32 v82, v226
	v_mov_b32_e32 v83, v230
	v_pk_fma_f32 v[54:55], v[82:83], v[82:83], v[54:55]
	v_mov_b32_e32 v82, v227
	v_mov_b32_e32 v83, v231
	v_pk_fma_f32 v[54:55], v[82:83], v[82:83], v[54:55]
	s_nop 0
	v_add_f32_e32 v54, v63, v54
	v_add_f32_e32 v54, v54, v55
	s_nop 1
	v_add_f32_dpp v54, v54, v54 quad_perm:[1,0,3,2] row_mask:0xf bank_mask:0xf
	s_nop 1
	v_add_f32_dpp v54, v54, v54 quad_perm:[2,3,0,1] row_mask:0xf bank_mask:0xf
	s_nop 1
	v_add_f32_dpp v54, v54, v54 row_half_mirror row_mask:0xf bank_mask:0xf
	s_nop 1
	v_add_f32_dpp v54, v54, v54 row_mirror row_mask:0xf bank_mask:0xf
	s_nop 1
	v_add_f32_dpp v54, v54, v54 row_bcast:15 row_mask:0xa bank_mask:0xf
	s_nop 1
	v_add_f32_dpp v54, v54, v54 row_bcast:31 row_mask:0xc bank_mask:0xf
	s_nop 1
	v_readlane_b32 s100, v54, 63
	s_nop 3
	v_mov_b32_e32 v54, s100
	v_fmamk_f32 v54, v54, 0x3a800000, v119
	v_cmp_gt_f32_e32 vcc, s9, v54
	v_mul_f32_e32 v55, 0x4b800000, v54
	s_nop 0
	v_cndmask_b32_e32 v54, v54, v55, vcc
	v_rsq_f32_e32 v54, v54
	s_nop 0
	v_mul_f32_e32 v55, 0x45800000, v54
	v_cndmask_b32_e32 v54, v54, v55, vcc
	s_waitcnt vmcnt(4)
	v_pk_mul_f32 v[64:65], v[64:65], v[54:55] op_sel_hi:[1,0]
	v_pk_mul_f32 v[66:67], v[66:67], v[54:55] op_sel_hi:[1,0]
	v_pk_fma_f32 v[64:65], v[38:39], v[64:65], v[28:29]
	v_pk_fma_f32 v[66:67], v[48:49], v[66:67], v[30:31]
	v_cvt_pk_bf16_f32 v64, v64, v65
	v_cvt_pk_bf16_f32 v65, v66, v67
	global_store_dwordx2 v[36:37], v[64:65], off
	v_pk_mul_f32 v[64:65], v[68:69], v[54:55] op_sel_hi:[1,0]
	v_pk_mul_f32 v[66:67], v[70:71], v[54:55] op_sel_hi:[1,0]
	v_pk_fma_f32 v[64:65], v[40:41], v[64:65], v[24:25]
	v_pk_fma_f32 v[66:67], v[42:43], v[66:67], v[26:27]
	v_cvt_pk_bf16_f32 v64, v64, v65
	v_cvt_pk_bf16_f32 v65, v66, v67
	global_store_dwordx2 v[36:37], v[64:65], off offset:512
	v_pk_mul_f32 v[64:65], v[224:225], v[54:55] op_sel_hi:[1,0]
	v_pk_mul_f32 v[66:67], v[226:227], v[54:55] op_sel_hi:[1,0]
	v_pk_fma_f32 v[64:65], v[44:45], v[64:65], v[20:21]
	v_pk_fma_f32 v[66:67], v[46:47], v[66:67], v[22:23]
	v_cvt_pk_bf16_f32 v64, v64, v65
	v_cvt_pk_bf16_f32 v65, v66, v67
	global_store_dwordx2 v[36:37], v[64:65], off offset:1024
	v_pk_mul_f32 v[64:65], v[228:229], v[54:55] op_sel_hi:[1,0]
	v_pk_mul_f32 v[54:55], v[230:231], v[54:55] op_sel_hi:[1,0]
	v_pk_fma_f32 v[64:65], v[50:51], v[64:65], v[16:17]
	v_pk_fma_f32 v[54:55], v[52:53], v[54:55], v[18:19]
	v_cvt_pk_bf16_f32 v64, v64, v65
	v_cvt_pk_bf16_f32 v65, v54, v55
	v_cmp_ge_i32_e32 vcc, v32, v35
	global_store_dwordx2 v[36:37], v[64:65], off offset:1536
	v_lshl_add_u64 v[36:37], v[36:37], 0, s[16:17]
	s_or_b64 s[38:39], vcc, s[38:39]
	s_andn2_b64 exec, exec, s[38:39]
	s_cbranch_execz .LBB0_1353
